# U pass second half-step: next-step gather issue points spread over 85% of the compute instead of 60%
# baseline (speedup 1.0000x reference)
.LBB0_928:
	s_waitcnt vmcnt(0)
	v_dot4_i32_i8 v138, v132, v80, 0
	v_dot4_i32_i8 v132, v128, v80, 0
	v_dot4_i32_i8 v128, v124, v80, 0
	v_dot4_i32_i8 v124, v120, v80, 0
	v_dot4_i32_i8 v120, v116, v80, 0
	global_load_dwordx4 v[0:3], v0, s[16:17]
	v_dot4_i32_i8 v116, v112, v80, 0
	v_dot4_i32_i8 v112, v108, v80, 0
	v_dot4_i32_i8 v108, v104, v80, 0
	v_dot4_i32_i8 v104, v100, v80, 0
	v_dot4_i32_i8 v100, v96, v80, 0
	v_dot4_i32_i8 v96, v92, v80, 0
	global_load_dwordx4 v[4:7], v4, s[16:17]
	v_dot4_i32_i8 v92, v88, v80, 0
	v_dot4_i32_i8 v88, v84, v80, 0
	v_dot4c_i32_i8_e32 v138, v133, v81
	v_dot4c_i32_i8_e32 v104, v101, v81
	v_dot4_i32_i8 v84, v76, v80, 0
	v_dot4c_i32_i8_e32 v138, v134, v82
	global_load_dwordx4 v[8:11], v8, s[16:17]
	v_dot4c_i32_i8_e32 v132, v129, v81
	v_dot4c_i32_i8_e32 v104, v102, v82
	v_dot4c_i32_i8_e32 v100, v97, v81
	v_dot4_i32_i8 v76, v72, v80, 0
	v_dot4c_i32_i8_e32 v138, v135, v83
	v_dot4c_i32_i8_e32 v132, v130, v82
	global_load_dwordx4 v[12:15], v12, s[16:17]
	v_dot4c_i32_i8_e32 v128, v125, v81
	v_dot4c_i32_i8_e32 v104, v103, v83
	v_dot4c_i32_i8_e32 v100, v98, v82
	v_dot4c_i32_i8_e32 v96, v93, v81
	v_dot4_i32_i8 v72, v68, v80, 0
	v_dot4c_i32_i8_e32 v132, v131, v83
	global_load_dwordx4 v[16:19], v16, s[16:17]
	v_dot4c_i32_i8_e32 v128, v126, v82
	v_dot4c_i32_i8_e32 v124, v121, v81
	v_dot4c_i32_i8_e32 v100, v99, v83
	v_dot4c_i32_i8_e32 v96, v94, v82
	v_dot4c_i32_i8_e32 v92, v89, v81
	v_dot4c_i32_i8_e32 v72, v69, v81
	global_load_dwordx4 v[20:23], v20, s[16:17]
	v_dot4c_i32_i8_e32 v128, v127, v83
	v_dot4c_i32_i8_e32 v124, v122, v82
	v_dot4c_i32_i8_e32 v120, v117, v81
	v_dot4c_i32_i8_e32 v96, v95, v83
	v_dot4c_i32_i8_e32 v92, v90, v82
	v_dot4c_i32_i8_e32 v88, v85, v81
	global_load_dwordx4 v[24:27], v24, s[16:17]
	v_dot4c_i32_i8_e32 v72, v70, v82
	v_dot4c_i32_i8_e32 v124, v123, v83
	v_dot4c_i32_i8_e32 v120, v118, v82
	v_dot4c_i32_i8_e32 v116, v113, v81
	v_dot4c_i32_i8_e32 v92, v91, v83
	v_dot4c_i32_i8_e32 v88, v86, v82
	global_load_dwordx4 v[28:31], v28, s[16:17]
	v_dot4c_i32_i8_e32 v84, v77, v81
	v_dot4c_i32_i8_e32 v72, v71, v83
	v_dot4c_i32_i8_e32 v120, v119, v83
	v_dot4c_i32_i8_e32 v116, v114, v82
	v_dot4c_i32_i8_e32 v88, v87, v83
	global_load_dwordx4 v[32:35], v32, s[16:17]
	v_dot4c_i32_i8_e32 v84, v78, v82
	v_dot4c_i32_i8_e32 v76, v73, v81
	v_dot4c_i32_i8_e32 v116, v115, v83
	v_dot4c_i32_i8_e32 v84, v79, v83
	v_dot4c_i32_i8_e32 v76, v74, v82
	v_dot4c_i32_i8_e32 v76, v75, v83
	global_load_dwordx4 v[36:39], v36, s[16:17]
	v_add_u32_dpp v68, v138, v138 row_ror:12 row_mask:0xf bank_mask:0x5
	v_add_u32_dpp v68, v104, v104 row_ror:4 row_mask:0xf bank_mask:0xa
	s_waitcnt lgkmcnt(4)
	v_add_u32_dpp v69, v132, v132 row_ror:12 row_mask:0xf bank_mask:0x5
	v_add_u32_dpp v69, v100, v100 row_ror:4 row_mask:0xf bank_mask:0xa
	s_waitcnt lgkmcnt(4)
	global_load_dwordx4 v[40:43], v40, s[16:17]
	v_add_u32_dpp v70, v128, v128 row_ror:12 row_mask:0xf bank_mask:0x5
	v_add_u32_dpp v70, v96, v96 row_ror:4 row_mask:0xf bank_mask:0xa
	v_dot4c_i32_i8_e32 v112, v109, v81
	v_dot4c_i32_i8_e32 v108, v105, v81
	s_waitcnt lgkmcnt(3)
	v_add_u32_dpp v71, v124, v124 row_ror:12 row_mask:0xf bank_mask:0x5
	global_load_dwordx4 v[44:47], v44, s[16:17]
	v_add_u32_dpp v71, v92, v92 row_ror:4 row_mask:0xf bank_mask:0xa
	v_dot4c_i32_i8_e32 v112, v110, v82
	v_dot4c_i32_i8_e32 v108, v106, v82
	s_waitcnt lgkmcnt(2)
	v_add_u32_dpp v73, v120, v120 row_ror:12 row_mask:0xf bank_mask:0x5
	v_add_u32_dpp v73, v88, v88 row_ror:4 row_mask:0xf bank_mask:0xa
	global_load_dwordx4 v[48:51], v48, s[16:17]
	v_dot4c_i32_i8_e32 v112, v111, v83
	v_dot4c_i32_i8_e32 v108, v107, v83
	s_waitcnt lgkmcnt(1)
	v_add_u32_dpp v74, v116, v116 row_ror:12 row_mask:0xf bank_mask:0x5
	v_add_u32_dpp v74, v84, v84 row_ror:4 row_mask:0xf bank_mask:0xa
	s_waitcnt lgkmcnt(0)
	global_load_dwordx4 v[52:55], v52, s[16:17]
	v_add_u32_dpp v75, v112, v112 row_ror:12 row_mask:0xf bank_mask:0x5
	v_add_u32_dpp v75, v76, v76 row_ror:4 row_mask:0xf bank_mask:0xa
	v_add_u32_dpp v72, v72, v72 row_ror:4 row_mask:0xf bank_mask:0xa
	v_add_u32_dpp v72, v108, v108 row_ror:12 row_mask:0xf bank_mask:0x5
	v_add_u32_dpp v234, v68, v68 quad_perm:[2,3,0,1] row_mask:0xf bank_mask:0xf
	v_add_u32_dpp v235, v73, v73 quad_perm:[2,3,0,1] row_mask:0xf bank_mask:0xf
	global_load_dwordx4 v[56:59], v56, s[16:17]
	v_cndmask_b32_e64 v68, v235, v234, s[4:5]
	s_waitcnt lgkmcnt(1)
	s_waitcnt lgkmcnt(0)
	v_add_u32_dpp v234, v69, v69 quad_perm:[2,3,0,1] row_mask:0xf bank_mask:0xf
	v_add_u32_dpp v235, v74, v74 quad_perm:[2,3,0,1] row_mask:0xf bank_mask:0xf
	v_cndmask_b32_e64 v73, v235, v234, s[4:5]
	global_load_dwordx4 v[60:63], v60, s[16:17]
	v_add_u32_dpp v234, v70, v70 quad_perm:[2,3,0,1] row_mask:0xf bank_mask:0xf
	v_add_u32_dpp v235, v75, v75 quad_perm:[2,3,0,1] row_mask:0xf bank_mask:0xf
	v_cndmask_b32_e64 v70, v235, v234, s[4:5]
	v_add_u32_dpp v234, v71, v71 quad_perm:[2,3,0,1] row_mask:0xf bank_mask:0xf
	v_add_u32_dpp v235, v72, v72 quad_perm:[2,3,0,1] row_mask:0xf bank_mask:0xf
	v_cndmask_b32_e64 v71, v235, v234, s[4:5]
	s_waitcnt lgkmcnt(3)
	s_waitcnt lgkmcnt(2)
	v_mov_b32_e32 v69, v73
	s_waitcnt lgkmcnt(1)
	s_waitcnt lgkmcnt(0)
	v_add_u32_dpp v234, v68, v68 quad_perm:[1,0,3,2] row_mask:0xf bank_mask:0xf
	v_add_u32_dpp v235, v70, v70 quad_perm:[1,0,3,2] row_mask:0xf bank_mask:0xf
	v_cndmask_b32_e64 v68, v235, v234, s[6:7]
	v_add_u32_dpp v234, v69, v69 quad_perm:[1,0,3,2] row_mask:0xf bank_mask:0xf
	v_add_u32_dpp v235, v71, v71 quad_perm:[1,0,3,2] row_mask:0xf bank_mask:0xf
	v_cndmask_b32_e64 v69, v235, v234, s[6:7]
	s_andn2_b64 vcc, exec, s[14:15]
	s_waitcnt lgkmcnt(1)
	s_waitcnt lgkmcnt(0)
	v_lshl_add_u32 v70, s65, 2, v190
	s_cbranch_vccnz .LBB0_923
	ds_read_b64 v[72:73], v70
	s_waitcnt lgkmcnt(0)
	v_add_u32_e32 v68, v72, v68
	v_add_u32_e32 v69, v73, v69
	s_branch .LBB0_923
